# grid barrier: pollers watch the global arrival counter (released when count reaches (gen+1)*num_xcd) instead of the separate release flag
# speedup vs baseline: 1.0044x; 1.0044x over previous
; __device__ __forceinline__ unsigned xb_ld(unsigned* p)              { return __hip_atomic_load(p, __ATOMIC_RELAXED, __HIP_MEMORY_SCOPE_AGENT); }
; __device__ __forceinline__ unsigned xb_add(unsigned* p, unsigned v) { return __hip_atomic_fetch_add(p, v, __ATOMIC_RELAXED, __HIP_MEMORY_SCOPE_AGENT); }
; #define XB_SPIN(cond, bar) do { unsigned _sp = 0; while (cond) { __builtin_amdgcn_s_sleep(1); \
;     if ((++_sp & 255u) == 0u) { if (xb_ld(&(bar)[XB_TMO])) break; if (_sp > XB_SPIN_CAP) { atomicAdd(&(bar)[XB_TMO], 1u); break; } } } } while (0)
; __device__ __forceinline__ void xcd_barrier(const XcdBarrier& b) {
;     ...
;         const unsigned old = xb_add(&bar[XB_XSUB(b.x)], 1u);
;         const unsigned gen = old / nloc;
;         if (old + 1u == (gen + 1u) * nloc) {
;             __builtin_amdgcn_fence(__ATOMIC_RELEASE, "agent");
;             asm volatile("s_waitcnt vmcnt(0)" ::: "memory");
;             const unsigned og = xb_add(&bar[XB_TOP], 1u);
;             const unsigned tg = og / nx;
;             if (og + 1u == (tg + 1u) * nx) xb_add(&bar[XB_TOPGEN], 1u);
;             else XB_SPIN(xb_ld(&bar[XB_TOPGEN]) == tg, bar);
;             __builtin_amdgcn_fence(__ATOMIC_ACQUIRE, "agent");
;             xb_add(&bar[XB_XGEN(b.x)], 1u);
;             asm volatile("s_waitcnt vmcnt(0)" ::: "memory");
;         } else {
;             XB_SPIN(xb_ld(&bar[XB_XGEN(b.x)]) == gen, bar);
.LBB0_59:
	s_lshl_b32 s6, s87, 8
	s_add_u32 s6, s88, s6
	s_addc_u32 s7, s89, 0
	v_mov_b32_e32 v1, 0x1000
	v_mov_b32_e32 v3, 1
	global_atomic_add v3, v1, v3, s[6:7] offset:1024 sc0
	buffer_inv sc1
	v_cvt_f32_u32_e32 v1, v2
	v_sub_u32_e32 v4, 0, v2
	v_rcp_iflag_f32_e32 v1, v1
	s_nop 0
	v_mul_f32_e32 v1, 0x4f7ffffe, v1
	v_cvt_u32_f32_e32 v1, v1
	v_mul_lo_u32 v4, v4, v1
	v_mul_hi_u32 v4, v1, v4
	v_add_u32_e32 v1, v1, v4
	s_waitcnt vmcnt(0)
	v_mul_hi_u32 v1, v3, v1
	v_mul_lo_u32 v4, v1, v2
	v_sub_u32_e32 v4, v3, v4
	v_add_u32_e32 v5, 1, v1
	v_cmp_ge_u32_e32 vcc, v4, v2
	v_add_u32_e32 v3, 1, v3
	s_nop 0
	v_cndmask_b32_e32 v1, v1, v5, vcc
	v_sub_u32_e32 v5, v4, v2
	v_cndmask_b32_e32 v4, v4, v5, vcc
	v_add_u32_e32 v5, 1, v1
	v_cmp_ge_u32_e32 vcc, v4, v2
	s_nop 1
	v_cndmask_b32_e32 v1, v1, v5, vcc
	v_mul_lo_u32 v4, v2, v1
	v_add_u32_e32 v2, v4, v2
	v_cmp_ne_u32_e32 vcc, v3, v2
	s_and_saveexec_b64 s[14:15], vcc
	s_xor_b64 s[14:15], exec, s[14:15]
	s_cbranch_execz .LBB0_73
	s_waitcnt lgkmcnt(0)
	v_mad_u32_u24 v1, v1, v0, v0
	v_mov_b32_e32 v0, 0x3400
	global_load_dword v0, v0, s[88:89] sc1
	s_add_u32 s20, s88, 0x3500
	s_addc_u32 s21, s89, 0
	s_waitcnt vmcnt(0)
	v_cmp_lt_u32_e32 vcc, v0, v1
	s_and_saveexec_b64 s[16:17], vcc
	s_cbranch_execz .LBB0_72
	s_add_u32 s18, s80, 0x10200
	s_addc_u32 s19, s81, 0
	s_mov_b32 s33, 1
	s_mov_b64 s[22:23], 0
	v_mov_b32_e32 v0, 0
	s_branch .LBB0_63

.LBB0_67:
	global_load_dword v2, v0, s[20:21] offset:-256 sc1
	s_add_i32 s33, s33, 1
	s_mov_b64 s[36:37], -1
	s_waitcnt vmcnt(0)
	v_cmp_ge_u32_e32 vcc, v2, v1
	s_orn2_b64 s[34:35], vcc, exec
	s_branch .LBB0_62

; __device__ __forceinline__ unsigned xb_ld(unsigned* p)              { return __hip_atomic_load(p, __ATOMIC_RELAXED, __HIP_MEMORY_SCOPE_AGENT); }
; __device__ __forceinline__ unsigned xb_add(unsigned* p, unsigned v) { return __hip_atomic_fetch_add(p, v, __ATOMIC_RELAXED, __HIP_MEMORY_SCOPE_AGENT); }
; #define XB_SPIN(cond, bar) do { unsigned _sp = 0; while (cond) { __builtin_amdgcn_s_sleep(1); \
;     if ((++_sp & 255u) == 0u) { if (xb_ld(&(bar)[XB_TMO])) break; if (_sp > XB_SPIN_CAP) { atomicAdd(&(bar)[XB_TMO], 1u); break; } } } } while (0)
; __device__ __forceinline__ void xcd_barrier(const XcdBarrier& b) {
;     ...
;             const unsigned og = xb_add(&bar[XB_TOP], 1u);
;             const unsigned tg = og / nx;
;             if (og + 1u == (tg + 1u) * nx) xb_add(&bar[XB_TOPGEN], 1u);
;             else XB_SPIN(xb_ld(&bar[XB_TOPGEN]) == tg, bar);
.LBB0_76:
	s_or_b64 exec, exec, s[16:17]
	v_cvt_f32_u32_e32 v3, v0
	s_waitcnt vmcnt(0)
	v_readfirstlane_b32 s14, v2
	s_add_u32 s16, s80, 0x13500
	s_addc_u32 s17, s81, 0
	v_rcp_iflag_f32_e32 v3, v3
	v_add_u32_e32 v1, s14, v1
	v_add_u32_e32 v4, 1, v1
	s_mov_b64 s[18:19], -1
	v_mul_f32_e32 v2, 0x4f7ffffe, v3
	v_cvt_u32_f32_e32 v2, v2
	v_sub_u32_e32 v3, 0, v0
	v_mul_lo_u32 v3, v3, v2
	v_mul_hi_u32 v3, v2, v3
	v_add_u32_e32 v2, v2, v3
	v_mul_hi_u32 v2, v1, v2
	v_mul_lo_u32 v3, v2, v0
	v_sub_u32_e32 v1, v1, v3
	v_add_u32_e32 v5, 1, v2
	v_cmp_ge_u32_e32 vcc, v1, v0
	v_sub_u32_e32 v3, v1, v0
	s_nop 0
	v_cndmask_b32_e32 v2, v2, v5, vcc
	v_cndmask_b32_e32 v1, v1, v3, vcc
	v_add_u32_e32 v3, 1, v2
	v_cmp_ge_u32_e32 vcc, v1, v0
	s_nop 1
	v_cndmask_b32_e32 v2, v2, v3, vcc
	v_mul_lo_u32 v1, v0, v2
	v_add_u32_e32 v0, v1, v0
	v_mov_b32_e32 v5, v0
	v_cmp_ne_u32_e32 vcc, v4, v0
	v_mov_b64_e32 v[0:1], s[16:17]
	s_and_saveexec_b64 s[14:15], vcc
	s_cbranch_execz .LBB0_88
	v_mov_b32_e32 v0, 0
	global_load_dword v1, v0, s[16:17] offset:-256 sc1
	s_mov_b64 s[22:23], 0
	s_waitcnt vmcnt(0)
	v_cmp_lt_u32_e32 vcc, v1, v5
	s_and_saveexec_b64 s[20:21], vcc
	s_cbranch_execz .LBB0_87
	s_add_u32 s18, s80, 0x10200
	s_addc_u32 s19, s81, 0
	s_mov_b32 s33, 1
	s_branch .LBB0_80

.LBB0_84:
	global_load_dword v1, v0, s[16:17] offset:-256 sc1
	s_add_i32 s33, s33, 1
	s_mov_b64 s[34:35], -1
	s_waitcnt vmcnt(0)
	v_cmp_ge_u32_e32 vcc, v1, v5
	s_orn2_b64 s[38:39], vcc, exec
	s_branch .LBB0_79

; __device__ __forceinline__ unsigned xb_ld(unsigned* p)              { return __hip_atomic_load(p, __ATOMIC_RELAXED, __HIP_MEMORY_SCOPE_AGENT); }
; __device__ __forceinline__ unsigned xb_add(unsigned* p, unsigned v) { return __hip_atomic_fetch_add(p, v, __ATOMIC_RELAXED, __HIP_MEMORY_SCOPE_AGENT); }
; #define XB_SPIN(cond, bar) do { unsigned _sp = 0; while (cond) { __builtin_amdgcn_s_sleep(1); \
;     if ((++_sp & 255u) == 0u) { if (xb_ld(&(bar)[XB_TMO])) break; if (_sp > XB_SPIN_CAP) { atomicAdd(&(bar)[XB_TMO], 1u); break; } } } } while (0)
; __device__ __forceinline__ void xcd_barrier(const XcdBarrier& b) {
;     ...
;         const unsigned old = xb_add(&bar[XB_XSUB(b.x)], 1u);
;         const unsigned gen = old / nloc;
;         if (old + 1u == (gen + 1u) * nloc) {
;             __builtin_amdgcn_fence(__ATOMIC_RELEASE, "agent");
;             asm volatile("s_waitcnt vmcnt(0)" ::: "memory");
;             const unsigned og = xb_add(&bar[XB_TOP], 1u);
;             const unsigned tg = og / nx;
;             if (og + 1u == (tg + 1u) * nx) xb_add(&bar[XB_TOPGEN], 1u);
;             else XB_SPIN(xb_ld(&bar[XB_TOPGEN]) == tg, bar);
;             __builtin_amdgcn_fence(__ATOMIC_ACQUIRE, "agent");
;             xb_add(&bar[XB_XGEN(b.x)], 1u);
;             asm volatile("s_waitcnt vmcnt(0)" ::: "memory");
;         } else {
;             XB_SPIN(xb_ld(&bar[XB_XGEN(b.x)]) == gen, bar);
.LBB0_527:
	s_lshl_b32 s4, s87, 8
	s_add_u32 s4, s88, s4
	s_addc_u32 s5, s89, 0
	v_mov_b32_e32 v1, 0x1000
	v_mov_b32_e32 v3, 1
	global_atomic_add v3, v1, v3, s[4:5] offset:1024 sc0
	buffer_inv sc1
	v_cvt_f32_u32_e32 v1, v2
	v_sub_u32_e32 v4, 0, v2
	v_rcp_iflag_f32_e32 v1, v1
	s_nop 0
	v_mul_f32_e32 v1, 0x4f7ffffe, v1
	v_cvt_u32_f32_e32 v1, v1
	v_mul_lo_u32 v4, v4, v1
	v_mul_hi_u32 v4, v1, v4
	v_add_u32_e32 v1, v1, v4
	s_waitcnt vmcnt(0)
	v_mul_hi_u32 v1, v3, v1
	v_mul_lo_u32 v4, v1, v2
	v_sub_u32_e32 v4, v3, v4
	v_add_u32_e32 v5, 1, v1
	v_cmp_ge_u32_e32 vcc, v4, v2
	v_add_u32_e32 v3, 1, v3
	s_nop 0
	v_cndmask_b32_e32 v1, v1, v5, vcc
	v_sub_u32_e32 v5, v4, v2
	v_cndmask_b32_e32 v4, v4, v5, vcc
	v_add_u32_e32 v5, 1, v1
	v_cmp_ge_u32_e32 vcc, v4, v2
	s_nop 1
	v_cndmask_b32_e32 v1, v1, v5, vcc
	v_mul_lo_u32 v4, v2, v1
	v_add_u32_e32 v2, v4, v2
	v_cmp_ne_u32_e32 vcc, v3, v2
	s_and_saveexec_b64 s[6:7], vcc
	s_xor_b64 s[6:7], exec, s[6:7]
	s_cbranch_execz .LBB0_541
	s_waitcnt lgkmcnt(0)
	v_mad_u32_u24 v1, v1, v0, v0
	v_mov_b32_e32 v0, 0x3400
	global_load_dword v0, v0, s[88:89] sc1
	s_add_u32 s12, s88, 0x3500
	s_addc_u32 s13, s89, 0
	s_waitcnt vmcnt(0)
	v_cmp_lt_u32_e32 vcc, v0, v1
	s_and_saveexec_b64 s[8:9], vcc
	s_cbranch_execz .LBB0_540
	s_add_u32 s10, s80, 0x10200
	s_addc_u32 s11, s81, 0
	s_mov_b32 s24, 1
	s_mov_b64 s[14:15], 0
	v_mov_b32_e32 v0, 0
	s_branch .LBB0_531

.LBB0_535:
	global_load_dword v2, v0, s[12:13] offset:-256 sc1
	s_add_i32 s24, s24, 1
	s_mov_b64 s[20:21], -1
	s_waitcnt vmcnt(0)
	v_cmp_ge_u32_e32 vcc, v2, v1
	s_orn2_b64 s[18:19], vcc, exec
	s_branch .LBB0_530

; __device__ __forceinline__ unsigned xb_ld(unsigned* p)              { return __hip_atomic_load(p, __ATOMIC_RELAXED, __HIP_MEMORY_SCOPE_AGENT); }
; __device__ __forceinline__ unsigned xb_add(unsigned* p, unsigned v) { return __hip_atomic_fetch_add(p, v, __ATOMIC_RELAXED, __HIP_MEMORY_SCOPE_AGENT); }
; #define XB_SPIN(cond, bar) do { unsigned _sp = 0; while (cond) { __builtin_amdgcn_s_sleep(1); \
;     if ((++_sp & 255u) == 0u) { if (xb_ld(&(bar)[XB_TMO])) break; if (_sp > XB_SPIN_CAP) { atomicAdd(&(bar)[XB_TMO], 1u); break; } } } } while (0)
; __device__ __forceinline__ void xcd_barrier(const XcdBarrier& b) {
;     ...
;             const unsigned og = xb_add(&bar[XB_TOP], 1u);
;             const unsigned tg = og / nx;
;             if (og + 1u == (tg + 1u) * nx) xb_add(&bar[XB_TOPGEN], 1u);
;             else XB_SPIN(xb_ld(&bar[XB_TOPGEN]) == tg, bar);
.LBB0_544:
	s_or_b64 exec, exec, s[8:9]
	v_cvt_f32_u32_e32 v3, v0
	s_waitcnt vmcnt(0)
	v_readfirstlane_b32 s6, v2
	s_add_u32 s8, s80, 0x13500
	s_addc_u32 s9, s81, 0
	v_rcp_iflag_f32_e32 v3, v3
	v_add_u32_e32 v1, s6, v1
	v_add_u32_e32 v4, 1, v1
	s_mov_b64 s[10:11], -1
	v_mul_f32_e32 v2, 0x4f7ffffe, v3
	v_cvt_u32_f32_e32 v2, v2
	v_sub_u32_e32 v3, 0, v0
	v_mul_lo_u32 v3, v3, v2
	v_mul_hi_u32 v3, v2, v3
	v_add_u32_e32 v2, v2, v3
	v_mul_hi_u32 v2, v1, v2
	v_mul_lo_u32 v3, v2, v0
	v_sub_u32_e32 v1, v1, v3
	v_add_u32_e32 v5, 1, v2
	v_cmp_ge_u32_e32 vcc, v1, v0
	v_sub_u32_e32 v3, v1, v0
	s_nop 0
	v_cndmask_b32_e32 v2, v2, v5, vcc
	v_cndmask_b32_e32 v1, v1, v3, vcc
	v_add_u32_e32 v3, 1, v2
	v_cmp_ge_u32_e32 vcc, v1, v0
	s_nop 1
	v_cndmask_b32_e32 v2, v2, v3, vcc
	v_mul_lo_u32 v1, v0, v2
	v_add_u32_e32 v0, v1, v0
	v_mov_b32_e32 v5, v0
	v_cmp_ne_u32_e32 vcc, v4, v0
	v_mov_b64_e32 v[0:1], s[8:9]
	s_and_saveexec_b64 s[6:7], vcc
	s_cbranch_execz .LBB0_556
	v_mov_b32_e32 v0, 0
	global_load_dword v1, v0, s[8:9] offset:-256 sc1
	s_mov_b64 s[14:15], 0
	s_waitcnt vmcnt(0)
	v_cmp_lt_u32_e32 vcc, v1, v5
	s_and_saveexec_b64 s[12:13], vcc
	s_cbranch_execz .LBB0_555
	s_add_u32 s10, s80, 0x10200
	s_addc_u32 s11, s81, 0
	s_mov_b32 s24, 1
	s_branch .LBB0_548

.LBB0_552:
	global_load_dword v1, v0, s[8:9] offset:-256 sc1
	s_add_i32 s24, s24, 1
	s_mov_b64 s[18:19], -1
	s_waitcnt vmcnt(0)
	v_cmp_ge_u32_e32 vcc, v1, v5
	s_orn2_b64 s[22:23], vcc, exec
	s_branch .LBB0_547
